# PREP: loop-invariant row-major write offset hoisted out of the chunk loop
# baseline (speedup 1.0000x reference)
.LBB0_393:
	s_or_b64 exec, exec, s[74:75]
	s_lshl_b64 s[2:3], s[2:3], 24
	s_lshl_b64 s[2:3], s[2:3], 1
	v_readlane_b32 s19, v254, 44
	s_waitcnt lgkmcnt(0)
	s_barrier
	s_add_u32 s78, s19, s2
	v_readlane_b32 s2, v254, 45
	v_lshlrev_b32_e32 v189, 8, v18
	v_mov_b32_e32 v14, 0
	s_mov_b32 s20, 1
	s_addc_u32 s79, s2, s3
	s_mov_b32 s21, 0
	s_movk_i32 s19, 0x800
	v_add_u32_e32 v190, v152, v189
	s_mov_b32 s36, 0
	v_mov_b32_e32 v15, v14
	v_mov_b32_e32 v16, v14
	v_mov_b32_e32 v17, v14
	v_mov_b32_e32 v18, v14
	v_mov_b32_e32 v19, v14
	v_mov_b32_e32 v20, v14
	v_mov_b32_e32 v21, v14
	v_add_u32_e32 v241, v156, v163
	v_add_u32_e32 v200, v146, v145
	v_sub_u32_e32 v242, v164, v143
	v_mad_u32_u24 v242, v145, 5, v242
	v_add_u32_e32 v242, 0x18d00, v242
	v_mul_u32_u24_e32 v243, 5, v145
	v_sub_u32_e32 v243, v143, v243
	v_mul_i32_i24_e32 v243, 0x47, v243
	v_ashrrev_i32_e32 v243, 1, v243
	v_add_u32_e32 v243, v181, v243
	v_add_u32_e32 v192, v144, v145
	v_add_u32_e32 v199, v150, v145
	v_mov_b32_e32 v244, 0x800
	v_mov_b32_e32 v245, 0xfffff800
	v_cndmask_b32_e64 v244, v244, v245, s[12:13]
	v_add_u32_e32 v244, v190, v244
	v_lshrrev_b32_e32 v246, 1, v143
	s_branch .LBB0_395

.Lpq0_q0:
	ds_read2st64_b32 v[40:41], v143 offset0:96 offset1:97
	ds_read2st64_b32 v[42:43], v143 offset0:98 offset1:99
	ds_read2st64_b32 v[44:45], v143 offset0:100 offset1:101
	ds_read2st64_b32 v[46:47], v143 offset0:102 offset1:103
	ds_read2st64_b32 v[48:49], v143 offset0:104 offset1:105
	ds_read2st64_b32 v[50:51], v143 offset0:106 offset1:107
	ds_read2st64_b32 v[52:53], v143 offset0:108 offset1:109
	ds_read2st64_b32 v[54:55], v143 offset0:110 offset1:111
	ds_read2st64_b32 v[56:57], v143 offset0:112 offset1:113
	ds_read2st64_b32 v[58:59], v143 offset0:114 offset1:115
	ds_read2st64_b32 v[60:61], v143 offset0:116 offset1:117
	ds_read2st64_b32 v[62:63], v143 offset0:118 offset1:119
	v_mov_b32_e32 v69, 0
	s_waitcnt lgkmcnt(11)
	v_add_f32_e32 v65, v69, v41
	s_waitcnt lgkmcnt(8)
	v_add_f32_e32 v66, v65, v47
	s_waitcnt lgkmcnt(5)
	v_add_f32_e32 v67, v66, v53
	s_waitcnt lgkmcnt(2)
	v_add_f32_e32 v68, v67, v59
	v_mul_f32_e32 v79, 0xbfb8aa3b, v69
	v_exp_f32_e32 v70, v79
	v_mul_f32_e32 v80, 0x3fb8aa3b, v65
	v_exp_f32_e32 v75, v80
	v_exp_f32_e64 v71, -v80
	v_mul_f32_e32 v97, 0x3fb8aa3b, v66
	v_exp_f32_e32 v76, v97
	v_exp_f32_e64 v72, -v97
	v_mul_f32_e32 v80, 0x3fb8aa3b, v67
	v_exp_f32_e32 v77, v80
	v_exp_f32_e64 v73, -v80
	v_mul_f32_e32 v97, 0x3fb8aa3b, v68
	v_exp_f32_e32 v78, v97
	v_exp_f32_e64 v74, -v97
	s_nop 0
	v_mul_f32_e32 v81, v70, v40
	v_mul_f32_e32 v85, v75, v43
	v_mul_f32_e32 v89, v75, v42
	v_mul_f32_e32 v93, v71, v44
	v_mul_f32_e32 v82, v71, v46
	v_mul_f32_e32 v86, v76, v49
	v_mul_f32_e32 v90, v76, v48
	v_mul_f32_e32 v94, v72, v50
	v_mul_f32_e32 v83, v72, v52
	v_mul_f32_e32 v87, v77, v55
	v_mul_f32_e32 v91, v77, v54
	v_mul_f32_e32 v95, v73, v56
	v_mul_f32_e32 v84, v73, v58
	s_waitcnt lgkmcnt(1)
	v_mul_f32_e32 v88, v78, v61
	v_mul_f32_e32 v92, v78, v60
	s_waitcnt lgkmcnt(0)
	v_mul_f32_e32 v96, v74, v62
	v_cvt_pk_bf16_f32 v112, v81, v82
	v_cvt_pk_bf16_f32 v113, v83, v84
	v_cvt_pk_bf16_f32 v114, v85, v86
	v_cvt_pk_bf16_f32 v115, v87, v88
	v_cvt_pk_bf16_f32 v116, v89, v90
	v_cvt_pk_bf16_f32 v117, v91, v92
	v_cvt_pk_bf16_f32 v118, v93, v94
	v_cvt_pk_bf16_f32 v119, v95, v96
	v_cvt_pk_bf16_f32 v120, v45, v51
	v_cvt_pk_bf16_f32 v121, v57, v63
	ds_write_b16 v246, v112 offset:51456
	ds_write_b16_d16_hi v246, v112 offset:51600
	ds_write_b16 v246, v113 offset:51744
	ds_write_b16_d16_hi v246, v113 offset:51888
	ds_write_b16 v246, v114 offset:53760
	ds_write_b16_d16_hi v246, v114 offset:53904
	ds_write_b16 v246, v115 offset:54048
	ds_write_b16_d16_hi v246, v115 offset:54192
	ds_write_b16 v246, v116 offset:56064
	ds_write_b16_d16_hi v246, v116 offset:56208
	ds_write_b16 v246, v117 offset:56352
	ds_write_b16_d16_hi v246, v117 offset:56496
	ds_write_b16 v246, v118 offset:60672
	ds_write_b16_d16_hi v246, v118 offset:60816
	ds_write_b16 v246, v119 offset:60960
	ds_write_b16_d16_hi v246, v119 offset:61104
	ds_write_b64 v139, v[114:115] offset:5120
	ds_write_b64 v139, v[116:117] offset:5152
	ds_write_b64 v140, v[120:121] offset:5152
	s_branch .Lpq0_end
.Lpq0_q1:
	ds_read2st64_b32 v[26:27], v143 offset0:97 offset1:103
	ds_read2st64_b32 v[28:29], v143 offset0:109 offset1:115
	ds_read2st64_b32 v[40:41], v143 offset0:120 offset1:121
	ds_read2st64_b32 v[42:43], v143 offset0:122 offset1:123
	ds_read2st64_b32 v[44:45], v143 offset0:124 offset1:125
	ds_read2st64_b32 v[46:47], v143 offset0:126 offset1:127
	ds_read2st64_b32 v[48:49], v143 offset0:128 offset1:129
	ds_read2st64_b32 v[50:51], v143 offset0:130 offset1:131
	ds_read2st64_b32 v[52:53], v143 offset0:132 offset1:133
	ds_read2st64_b32 v[54:55], v143 offset0:134 offset1:135
	ds_read2st64_b32 v[56:57], v143 offset0:136 offset1:137
	ds_read2st64_b32 v[58:59], v143 offset0:138 offset1:139
	ds_read2st64_b32 v[60:61], v143 offset0:140 offset1:141
	ds_read2st64_b32 v[62:63], v143 offset0:142 offset1:143
	s_waitcnt lgkmcnt(13)
	v_add_f32_e32 v69, v26, v27
	s_waitcnt lgkmcnt(12)
	v_add_f32_e32 v69, v69, v28
	v_add_f32_e32 v69, v69, v29
	s_waitcnt lgkmcnt(11)
	v_add_f32_e32 v65, v69, v41
	s_waitcnt lgkmcnt(8)
	v_add_f32_e32 v66, v65, v47
	s_waitcnt lgkmcnt(5)
	v_add_f32_e32 v67, v66, v53
	s_waitcnt lgkmcnt(2)
	v_add_f32_e32 v68, v67, v59
	v_mul_f32_e32 v79, 0xbfb8aa3b, v69
	v_exp_f32_e32 v70, v79
	v_mul_f32_e32 v80, 0x3fb8aa3b, v65
	v_exp_f32_e32 v75, v80
	v_exp_f32_e64 v71, -v80
	v_mul_f32_e32 v97, 0x3fb8aa3b, v66
	v_exp_f32_e32 v76, v97
	v_exp_f32_e64 v72, -v97
	v_mul_f32_e32 v80, 0x3fb8aa3b, v67
	v_exp_f32_e32 v77, v80
	v_exp_f32_e64 v73, -v80
	v_mul_f32_e32 v97, 0x3fb8aa3b, v68
	v_exp_f32_e32 v78, v97
	v_exp_f32_e64 v74, -v97
	s_nop 0
	v_mul_f32_e32 v81, v70, v40
	v_mul_f32_e32 v85, v75, v43
	v_mul_f32_e32 v89, v75, v42
	v_mul_f32_e32 v93, v71, v44
	v_mul_f32_e32 v82, v71, v46
	v_mul_f32_e32 v86, v76, v49
	v_mul_f32_e32 v90, v76, v48
	v_mul_f32_e32 v94, v72, v50
	v_mul_f32_e32 v83, v72, v52
	v_mul_f32_e32 v87, v77, v55
	v_mul_f32_e32 v91, v77, v54
	v_mul_f32_e32 v95, v73, v56
	v_mul_f32_e32 v84, v73, v58
	s_waitcnt lgkmcnt(1)
	v_mul_f32_e32 v88, v78, v61
	v_mul_f32_e32 v92, v78, v60
	s_waitcnt lgkmcnt(0)
	v_mul_f32_e32 v96, v74, v62
	v_cvt_pk_bf16_f32 v112, v81, v82
	v_cvt_pk_bf16_f32 v113, v83, v84
	v_cvt_pk_bf16_f32 v114, v85, v86
	v_cvt_pk_bf16_f32 v115, v87, v88
	v_cvt_pk_bf16_f32 v116, v89, v90
	v_cvt_pk_bf16_f32 v117, v91, v92
	v_cvt_pk_bf16_f32 v118, v93, v94
	v_cvt_pk_bf16_f32 v119, v95, v96
	v_cvt_pk_bf16_f32 v120, v45, v51
	v_cvt_pk_bf16_f32 v121, v57, v63
	ds_write_b16 v246, v112 offset:52032
	ds_write_b16_d16_hi v246, v112 offset:52176
	ds_write_b16 v246, v113 offset:52320
	ds_write_b16_d16_hi v246, v113 offset:52464
	ds_write_b16 v246, v114 offset:54336
	ds_write_b16_d16_hi v246, v114 offset:54480
	ds_write_b16 v246, v115 offset:54624
	ds_write_b16_d16_hi v246, v115 offset:54768
	ds_write_b16 v246, v116 offset:56640
	ds_write_b16_d16_hi v246, v116 offset:56784
	ds_write_b16 v246, v117 offset:56928
	ds_write_b16_d16_hi v246, v117 offset:57072
	ds_write_b16 v246, v118 offset:61248
	ds_write_b16_d16_hi v246, v118 offset:61392
	ds_write_b16 v246, v119 offset:61536
	ds_write_b16_d16_hi v246, v119 offset:61680
	ds_write_b64 v139, v[114:115] offset:5128
	ds_write_b64 v139, v[116:117] offset:5160
	ds_write_b64 v140, v[120:121] offset:5160
	s_branch .Lpq0_end
.Lpq0_q2:
	ds_read2st64_b32 v[26:27], v143 offset0:97 offset1:103
	ds_read2st64_b32 v[28:29], v143 offset0:109 offset1:115
	ds_read2st64_b32 v[30:31], v143 offset0:121 offset1:127
	ds_read2st64_b32 v[32:33], v143 offset0:133 offset1:139
	ds_read2st64_b32 v[40:41], v143 offset0:144 offset1:145
	ds_read2st64_b32 v[42:43], v143 offset0:146 offset1:147
	ds_read2st64_b32 v[44:45], v143 offset0:148 offset1:149
	ds_read2st64_b32 v[46:47], v143 offset0:150 offset1:151
	ds_read2st64_b32 v[48:49], v143 offset0:152 offset1:153
	ds_read2st64_b32 v[50:51], v143 offset0:154 offset1:155
	ds_read2st64_b32 v[52:53], v143 offset0:156 offset1:157
	ds_read2st64_b32 v[54:55], v143 offset0:158 offset1:159
	ds_read2st64_b32 v[56:57], v143 offset0:160 offset1:161
	ds_read2st64_b32 v[58:59], v143 offset0:162 offset1:163
	ds_read2st64_b32 v[60:61], v143 offset0:164 offset1:165
	s_waitcnt lgkmcnt(14)
	ds_read2st64_b32 v[62:63], v143 offset0:166 offset1:167
	v_add_f32_e32 v69, v26, v27
	s_waitcnt lgkmcnt(14)
	v_add_f32_e32 v69, v69, v28
	v_add_f32_e32 v69, v69, v29
	s_waitcnt lgkmcnt(13)
	v_add_f32_e32 v69, v69, v30
	v_add_f32_e32 v69, v69, v31
	s_waitcnt lgkmcnt(12)
	v_add_f32_e32 v69, v69, v32
	v_add_f32_e32 v69, v69, v33
	s_waitcnt lgkmcnt(11)
	v_add_f32_e32 v65, v69, v41
	s_waitcnt lgkmcnt(8)
	v_add_f32_e32 v66, v65, v47
	s_waitcnt lgkmcnt(5)
	v_add_f32_e32 v67, v66, v53
	s_waitcnt lgkmcnt(2)
	v_add_f32_e32 v68, v67, v59
	v_mul_f32_e32 v79, 0xbfb8aa3b, v69
	v_exp_f32_e32 v70, v79
	v_mul_f32_e32 v80, 0x3fb8aa3b, v65
	v_exp_f32_e32 v75, v80
	v_exp_f32_e64 v71, -v80
	v_mul_f32_e32 v97, 0x3fb8aa3b, v66
	v_exp_f32_e32 v76, v97
	v_exp_f32_e64 v72, -v97
	v_mul_f32_e32 v80, 0x3fb8aa3b, v67
	v_exp_f32_e32 v77, v80
	v_exp_f32_e64 v73, -v80
	v_mul_f32_e32 v97, 0x3fb8aa3b, v68
	v_exp_f32_e32 v78, v97
	v_exp_f32_e64 v74, -v97
	s_nop 0
	v_mul_f32_e32 v81, v70, v40
	v_mul_f32_e32 v85, v75, v43
	v_mul_f32_e32 v89, v75, v42
	v_mul_f32_e32 v93, v71, v44
	v_mul_f32_e32 v82, v71, v46
	v_mul_f32_e32 v86, v76, v49
	v_mul_f32_e32 v90, v76, v48
	v_mul_f32_e32 v94, v72, v50
	v_mul_f32_e32 v83, v72, v52
	v_mul_f32_e32 v87, v77, v55
	v_mul_f32_e32 v91, v77, v54
	v_mul_f32_e32 v95, v73, v56
	v_mul_f32_e32 v84, v73, v58
	s_waitcnt lgkmcnt(1)
	v_mul_f32_e32 v88, v78, v61
	v_mul_f32_e32 v92, v78, v60
	s_waitcnt lgkmcnt(0)
	v_mul_f32_e32 v96, v74, v62
	v_cvt_pk_bf16_f32 v112, v81, v82
	v_cvt_pk_bf16_f32 v113, v83, v84
	v_cvt_pk_bf16_f32 v114, v85, v86
	v_cvt_pk_bf16_f32 v115, v87, v88
	v_cvt_pk_bf16_f32 v116, v89, v90
	v_cvt_pk_bf16_f32 v117, v91, v92
	v_cvt_pk_bf16_f32 v118, v93, v94
	v_cvt_pk_bf16_f32 v119, v95, v96
	v_cvt_pk_bf16_f32 v120, v45, v51
	v_cvt_pk_bf16_f32 v121, v57, v63
	ds_write_b16 v246, v112 offset:52608
	ds_write_b16_d16_hi v246, v112 offset:52752
	ds_write_b16 v246, v113 offset:52896
	ds_write_b16_d16_hi v246, v113 offset:53040
	ds_write_b16 v246, v114 offset:54912
	ds_write_b16_d16_hi v246, v114 offset:55056
	ds_write_b16 v246, v115 offset:55200
	ds_write_b16_d16_hi v246, v115 offset:55344
	ds_write_b16 v246, v116 offset:57216
	ds_write_b16_d16_hi v246, v116 offset:57360
	ds_write_b16 v246, v117 offset:57504
	ds_write_b16_d16_hi v246, v117 offset:57648
	ds_write_b16 v246, v118 offset:61824
	ds_write_b16_d16_hi v246, v118 offset:61968
	ds_write_b16 v246, v119 offset:62112
	ds_write_b16_d16_hi v246, v119 offset:62256
	ds_write_b64 v139, v[114:115] offset:5136
	ds_write_b64 v139, v[116:117] offset:5168
	ds_write_b64 v140, v[120:121] offset:5168
	s_branch .Lpq0_end
.Lpq0_q3:
	ds_read2st64_b32 v[26:27], v143 offset0:97 offset1:103
	ds_read2st64_b32 v[28:29], v143 offset0:109 offset1:115
	ds_read2st64_b32 v[30:31], v143 offset0:121 offset1:127
	ds_read2st64_b32 v[32:33], v143 offset0:133 offset1:139
	ds_read2st64_b32 v[34:35], v143 offset0:145 offset1:151
	ds_read2st64_b32 v[36:37], v143 offset0:157 offset1:163
	ds_read2st64_b32 v[40:41], v143 offset0:168 offset1:169
	ds_read2st64_b32 v[42:43], v143 offset0:170 offset1:171
	ds_read2st64_b32 v[44:45], v143 offset0:172 offset1:173
	ds_read2st64_b32 v[46:47], v143 offset0:174 offset1:175
	ds_read2st64_b32 v[48:49], v143 offset0:176 offset1:177
	ds_read2st64_b32 v[50:51], v143 offset0:178 offset1:179
	ds_read2st64_b32 v[52:53], v143 offset0:180 offset1:181
	ds_read2st64_b32 v[54:55], v143 offset0:182 offset1:183
	ds_read2st64_b32 v[56:57], v143 offset0:184 offset1:185
	s_waitcnt lgkmcnt(14)
	ds_read2st64_b32 v[58:59], v143 offset0:186 offset1:187
	s_waitcnt lgkmcnt(14)
	ds_read2st64_b32 v[60:61], v143 offset0:188 offset1:189
	s_waitcnt lgkmcnt(14)
	ds_read2st64_b32 v[62:63], v143 offset0:190 offset1:191
	v_add_f32_e32 v69, v26, v27
	v_add_f32_e32 v69, v69, v28
	v_add_f32_e32 v69, v69, v29
	v_add_f32_e32 v69, v69, v30
	v_add_f32_e32 v69, v69, v31
	s_waitcnt lgkmcnt(14)
	v_add_f32_e32 v69, v69, v32
	v_add_f32_e32 v69, v69, v33
	s_waitcnt lgkmcnt(13)
	v_add_f32_e32 v69, v69, v34
	v_add_f32_e32 v69, v69, v35
	s_waitcnt lgkmcnt(12)
	v_add_f32_e32 v69, v69, v36
	v_add_f32_e32 v69, v69, v37
	s_waitcnt lgkmcnt(11)
	v_add_f32_e32 v65, v69, v41
	s_waitcnt lgkmcnt(8)
	v_add_f32_e32 v66, v65, v47
	s_waitcnt lgkmcnt(5)
	v_add_f32_e32 v67, v66, v53
	s_waitcnt lgkmcnt(2)
	v_add_f32_e32 v68, v67, v59
	v_mul_f32_e32 v79, 0xbfb8aa3b, v69
	v_exp_f32_e32 v70, v79
	v_mul_f32_e32 v80, 0x3fb8aa3b, v65
	v_exp_f32_e32 v75, v80
	v_exp_f32_e64 v71, -v80
	v_mul_f32_e32 v97, 0x3fb8aa3b, v66
	v_exp_f32_e32 v76, v97
	v_exp_f32_e64 v72, -v97
	v_mul_f32_e32 v80, 0x3fb8aa3b, v67
	v_exp_f32_e32 v77, v80
	v_exp_f32_e64 v73, -v80
	v_mul_f32_e32 v97, 0x3fb8aa3b, v68
	v_exp_f32_e32 v78, v97
	v_exp_f32_e64 v74, -v97
	s_nop 0
	v_mul_f32_e32 v81, v70, v40
	v_mul_f32_e32 v85, v75, v43
	v_mul_f32_e32 v89, v75, v42
	v_mul_f32_e32 v93, v71, v44
	v_mul_f32_e32 v82, v71, v46
	v_mul_f32_e32 v86, v76, v49
	v_mul_f32_e32 v90, v76, v48
	v_mul_f32_e32 v94, v72, v50
	v_mul_f32_e32 v83, v72, v52
	v_mul_f32_e32 v87, v77, v55
	v_mul_f32_e32 v91, v77, v54
	v_mul_f32_e32 v95, v73, v56
	v_mul_f32_e32 v84, v73, v58
	s_waitcnt lgkmcnt(1)
	v_mul_f32_e32 v88, v78, v61
	v_mul_f32_e32 v92, v78, v60
	s_waitcnt lgkmcnt(0)
	v_mul_f32_e32 v96, v74, v62
	v_cvt_pk_bf16_f32 v112, v81, v82
	v_cvt_pk_bf16_f32 v113, v83, v84
	v_cvt_pk_bf16_f32 v114, v85, v86
	v_cvt_pk_bf16_f32 v115, v87, v88
	v_cvt_pk_bf16_f32 v116, v89, v90
	v_cvt_pk_bf16_f32 v117, v91, v92
	v_cvt_pk_bf16_f32 v118, v93, v94
	v_cvt_pk_bf16_f32 v119, v95, v96
	v_cvt_pk_bf16_f32 v120, v45, v51
	v_cvt_pk_bf16_f32 v121, v57, v63
	ds_write_b16 v246, v112 offset:53184
	ds_write_b16_d16_hi v246, v112 offset:53328
	ds_write_b16 v246, v113 offset:53472
	ds_write_b16_d16_hi v246, v113 offset:53616
	ds_write_b16 v246, v114 offset:55488
	ds_write_b16_d16_hi v246, v114 offset:55632
	ds_write_b16 v246, v115 offset:55776
	ds_write_b16_d16_hi v246, v115 offset:55920
	ds_write_b16 v246, v116 offset:57792
	ds_write_b16_d16_hi v246, v116 offset:57936
	ds_write_b16 v246, v117 offset:58080
	ds_write_b16_d16_hi v246, v117 offset:58224
	ds_write_b16 v246, v118 offset:62400
	ds_write_b16_d16_hi v246, v118 offset:62544
	ds_write_b16 v246, v119 offset:62688
	ds_write_b16_d16_hi v246, v119 offset:62832
	ds_write_b64 v139, v[114:115] offset:5144
	ds_write_b64 v139, v[116:117] offset:5176
	ds_write_b64 v140, v[120:121] offset:5176
	v_add_u32_e32 v123, 0x18e00, v143
	ds_write_b32 v123, v74
	s_branch .Lpq0_end

.Lpq1_q0:
	ds_read2st64_b32 v[40:41], v143 offset0:0 offset1:1
	ds_read2st64_b32 v[42:43], v143 offset0:2 offset1:3
	ds_read2st64_b32 v[44:45], v143 offset0:4 offset1:5
	ds_read2st64_b32 v[46:47], v143 offset0:6 offset1:7
	ds_read2st64_b32 v[48:49], v143 offset0:8 offset1:9
	ds_read2st64_b32 v[50:51], v143 offset0:10 offset1:11
	ds_read2st64_b32 v[52:53], v143 offset0:12 offset1:13
	ds_read2st64_b32 v[54:55], v143 offset0:14 offset1:15
	ds_read2st64_b32 v[56:57], v143 offset0:16 offset1:17
	ds_read2st64_b32 v[58:59], v143 offset0:18 offset1:19
	ds_read2st64_b32 v[60:61], v143 offset0:20 offset1:21
	ds_read2st64_b32 v[62:63], v143 offset0:22 offset1:23
	v_mov_b32_e32 v69, 0
	s_waitcnt lgkmcnt(11)
	v_add_f32_e32 v65, v69, v41
	s_waitcnt lgkmcnt(8)
	v_add_f32_e32 v66, v65, v47
	s_waitcnt lgkmcnt(5)
	v_add_f32_e32 v67, v66, v53
	s_waitcnt lgkmcnt(2)
	v_add_f32_e32 v68, v67, v59
	v_mul_f32_e32 v79, 0xbfb8aa3b, v69
	v_exp_f32_e32 v70, v79
	v_mul_f32_e32 v80, 0x3fb8aa3b, v65
	v_exp_f32_e32 v75, v80
	v_exp_f32_e64 v71, -v80
	v_mul_f32_e32 v97, 0x3fb8aa3b, v66
	v_exp_f32_e32 v76, v97
	v_exp_f32_e64 v72, -v97
	v_mul_f32_e32 v80, 0x3fb8aa3b, v67
	v_exp_f32_e32 v77, v80
	v_exp_f32_e64 v73, -v80
	v_mul_f32_e32 v97, 0x3fb8aa3b, v68
	v_exp_f32_e32 v78, v97
	v_exp_f32_e64 v74, -v97
	s_nop 0
	v_mul_f32_e32 v81, v70, v40
	v_mul_f32_e32 v85, v75, v43
	v_mul_f32_e32 v89, v75, v42
	v_mul_f32_e32 v93, v71, v44
	v_mul_f32_e32 v82, v71, v46
	v_mul_f32_e32 v86, v76, v49
	v_mul_f32_e32 v90, v76, v48
	v_mul_f32_e32 v94, v72, v50
	v_mul_f32_e32 v83, v72, v52
	v_mul_f32_e32 v87, v77, v55
	v_mul_f32_e32 v91, v77, v54
	v_mul_f32_e32 v95, v73, v56
	v_mul_f32_e32 v84, v73, v58
	s_waitcnt lgkmcnt(1)
	v_mul_f32_e32 v88, v78, v61
	v_mul_f32_e32 v92, v78, v60
	s_waitcnt lgkmcnt(0)
	v_mul_f32_e32 v96, v74, v62
	v_cvt_pk_bf16_f32 v112, v81, v82
	v_cvt_pk_bf16_f32 v113, v83, v84
	v_cvt_pk_bf16_f32 v114, v85, v86
	v_cvt_pk_bf16_f32 v115, v87, v88
	v_cvt_pk_bf16_f32 v116, v89, v90
	v_cvt_pk_bf16_f32 v117, v91, v92
	v_cvt_pk_bf16_f32 v118, v93, v94
	v_cvt_pk_bf16_f32 v119, v95, v96
	v_cvt_pk_bf16_f32 v120, v45, v51
	v_cvt_pk_bf16_f32 v121, v57, v63
	ds_write_b16 v246, v112 offset:49152
	ds_write_b16_d16_hi v246, v112 offset:49296
	ds_write_b16 v246, v113 offset:49440
	ds_write_b16_d16_hi v246, v113 offset:49584
	ds_write_b16 v246, v114 offset:53760
	ds_write_b16_d16_hi v246, v114 offset:53904
	ds_write_b16 v246, v115 offset:54048
	ds_write_b16_d16_hi v246, v115 offset:54192
	ds_write_b16 v246, v116 offset:56064
	ds_write_b16_d16_hi v246, v116 offset:56208
	ds_write_b16 v246, v117 offset:56352
	ds_write_b16_d16_hi v246, v117 offset:56496
	ds_write_b16 v246, v118 offset:58368
	ds_write_b16_d16_hi v246, v118 offset:58512
	ds_write_b16 v246, v119 offset:58656
	ds_write_b16_d16_hi v246, v119 offset:58800
	ds_write_b64 v139, v[114:115] offset:0
	ds_write_b64 v139, v[116:117] offset:32
	ds_write_b64 v140, v[120:121] offset:32
	s_branch .Lpq1_end
.Lpq1_q1:
	ds_read2st64_b32 v[26:27], v143 offset0:1 offset1:7
	ds_read2st64_b32 v[28:29], v143 offset0:13 offset1:19
	ds_read2st64_b32 v[40:41], v143 offset0:24 offset1:25
	ds_read2st64_b32 v[42:43], v143 offset0:26 offset1:27
	ds_read2st64_b32 v[44:45], v143 offset0:28 offset1:29
	ds_read2st64_b32 v[46:47], v143 offset0:30 offset1:31
	ds_read2st64_b32 v[48:49], v143 offset0:32 offset1:33
	ds_read2st64_b32 v[50:51], v143 offset0:34 offset1:35
	ds_read2st64_b32 v[52:53], v143 offset0:36 offset1:37
	ds_read2st64_b32 v[54:55], v143 offset0:38 offset1:39
	ds_read2st64_b32 v[56:57], v143 offset0:40 offset1:41
	ds_read2st64_b32 v[58:59], v143 offset0:42 offset1:43
	ds_read2st64_b32 v[60:61], v143 offset0:44 offset1:45
	ds_read2st64_b32 v[62:63], v143 offset0:46 offset1:47
	s_waitcnt lgkmcnt(13)
	v_add_f32_e32 v69, v26, v27
	s_waitcnt lgkmcnt(12)
	v_add_f32_e32 v69, v69, v28
	v_add_f32_e32 v69, v69, v29
	s_waitcnt lgkmcnt(11)
	v_add_f32_e32 v65, v69, v41
	s_waitcnt lgkmcnt(8)
	v_add_f32_e32 v66, v65, v47
	s_waitcnt lgkmcnt(5)
	v_add_f32_e32 v67, v66, v53
	s_waitcnt lgkmcnt(2)
	v_add_f32_e32 v68, v67, v59
	v_mul_f32_e32 v79, 0xbfb8aa3b, v69
	v_exp_f32_e32 v70, v79
	v_mul_f32_e32 v80, 0x3fb8aa3b, v65
	v_exp_f32_e32 v75, v80
	v_exp_f32_e64 v71, -v80
	v_mul_f32_e32 v97, 0x3fb8aa3b, v66
	v_exp_f32_e32 v76, v97
	v_exp_f32_e64 v72, -v97
	v_mul_f32_e32 v80, 0x3fb8aa3b, v67
	v_exp_f32_e32 v77, v80
	v_exp_f32_e64 v73, -v80
	v_mul_f32_e32 v97, 0x3fb8aa3b, v68
	v_exp_f32_e32 v78, v97
	v_exp_f32_e64 v74, -v97
	s_nop 0
	v_mul_f32_e32 v81, v70, v40
	v_mul_f32_e32 v85, v75, v43
	v_mul_f32_e32 v89, v75, v42
	v_mul_f32_e32 v93, v71, v44
	v_mul_f32_e32 v82, v71, v46
	v_mul_f32_e32 v86, v76, v49
	v_mul_f32_e32 v90, v76, v48
	v_mul_f32_e32 v94, v72, v50
	v_mul_f32_e32 v83, v72, v52
	v_mul_f32_e32 v87, v77, v55
	v_mul_f32_e32 v91, v77, v54
	v_mul_f32_e32 v95, v73, v56
	v_mul_f32_e32 v84, v73, v58
	s_waitcnt lgkmcnt(1)
	v_mul_f32_e32 v88, v78, v61
	v_mul_f32_e32 v92, v78, v60
	s_waitcnt lgkmcnt(0)
	v_mul_f32_e32 v96, v74, v62
	v_cvt_pk_bf16_f32 v112, v81, v82
	v_cvt_pk_bf16_f32 v113, v83, v84
	v_cvt_pk_bf16_f32 v114, v85, v86
	v_cvt_pk_bf16_f32 v115, v87, v88
	v_cvt_pk_bf16_f32 v116, v89, v90
	v_cvt_pk_bf16_f32 v117, v91, v92
	v_cvt_pk_bf16_f32 v118, v93, v94
	v_cvt_pk_bf16_f32 v119, v95, v96
	v_cvt_pk_bf16_f32 v120, v45, v51
	v_cvt_pk_bf16_f32 v121, v57, v63
	ds_write_b16 v246, v112 offset:49728
	ds_write_b16_d16_hi v246, v112 offset:49872
	ds_write_b16 v246, v113 offset:50016
	ds_write_b16_d16_hi v246, v113 offset:50160
	ds_write_b16 v246, v114 offset:54336
	ds_write_b16_d16_hi v246, v114 offset:54480
	ds_write_b16 v246, v115 offset:54624
	ds_write_b16_d16_hi v246, v115 offset:54768
	ds_write_b16 v246, v116 offset:56640
	ds_write_b16_d16_hi v246, v116 offset:56784
	ds_write_b16 v246, v117 offset:56928
	ds_write_b16_d16_hi v246, v117 offset:57072
	ds_write_b16 v246, v118 offset:58944
	ds_write_b16_d16_hi v246, v118 offset:59088
	ds_write_b16 v246, v119 offset:59232
	ds_write_b16_d16_hi v246, v119 offset:59376
	ds_write_b64 v139, v[114:115] offset:8
	ds_write_b64 v139, v[116:117] offset:40
	ds_write_b64 v140, v[120:121] offset:40
	s_branch .Lpq1_end
.Lpq1_q2:
	ds_read2st64_b32 v[26:27], v143 offset0:1 offset1:7
	ds_read2st64_b32 v[28:29], v143 offset0:13 offset1:19
	ds_read2st64_b32 v[30:31], v143 offset0:25 offset1:31
	ds_read2st64_b32 v[32:33], v143 offset0:37 offset1:43
	ds_read2st64_b32 v[40:41], v143 offset0:48 offset1:49
	ds_read2st64_b32 v[42:43], v143 offset0:50 offset1:51
	ds_read2st64_b32 v[44:45], v143 offset0:52 offset1:53
	ds_read2st64_b32 v[46:47], v143 offset0:54 offset1:55
	ds_read2st64_b32 v[48:49], v143 offset0:56 offset1:57
	ds_read2st64_b32 v[50:51], v143 offset0:58 offset1:59
	ds_read2st64_b32 v[52:53], v143 offset0:60 offset1:61
	ds_read2st64_b32 v[54:55], v143 offset0:62 offset1:63
	ds_read2st64_b32 v[56:57], v143 offset0:64 offset1:65
	ds_read2st64_b32 v[58:59], v143 offset0:66 offset1:67
	ds_read2st64_b32 v[60:61], v143 offset0:68 offset1:69
	s_waitcnt lgkmcnt(14)
	ds_read2st64_b32 v[62:63], v143 offset0:70 offset1:71
	v_add_f32_e32 v69, v26, v27
	s_waitcnt lgkmcnt(14)
	v_add_f32_e32 v69, v69, v28
	v_add_f32_e32 v69, v69, v29
	s_waitcnt lgkmcnt(13)
	v_add_f32_e32 v69, v69, v30
	v_add_f32_e32 v69, v69, v31
	s_waitcnt lgkmcnt(12)
	v_add_f32_e32 v69, v69, v32
	v_add_f32_e32 v69, v69, v33
	s_waitcnt lgkmcnt(11)
	v_add_f32_e32 v65, v69, v41
	s_waitcnt lgkmcnt(8)
	v_add_f32_e32 v66, v65, v47
	s_waitcnt lgkmcnt(5)
	v_add_f32_e32 v67, v66, v53
	s_waitcnt lgkmcnt(2)
	v_add_f32_e32 v68, v67, v59
	v_mul_f32_e32 v79, 0xbfb8aa3b, v69
	v_exp_f32_e32 v70, v79
	v_mul_f32_e32 v80, 0x3fb8aa3b, v65
	v_exp_f32_e32 v75, v80
	v_exp_f32_e64 v71, -v80
	v_mul_f32_e32 v97, 0x3fb8aa3b, v66
	v_exp_f32_e32 v76, v97
	v_exp_f32_e64 v72, -v97
	v_mul_f32_e32 v80, 0x3fb8aa3b, v67
	v_exp_f32_e32 v77, v80
	v_exp_f32_e64 v73, -v80
	v_mul_f32_e32 v97, 0x3fb8aa3b, v68
	v_exp_f32_e32 v78, v97
	v_exp_f32_e64 v74, -v97
	s_nop 0
	v_mul_f32_e32 v81, v70, v40
	v_mul_f32_e32 v85, v75, v43
	v_mul_f32_e32 v89, v75, v42
	v_mul_f32_e32 v93, v71, v44
	v_mul_f32_e32 v82, v71, v46
	v_mul_f32_e32 v86, v76, v49
	v_mul_f32_e32 v90, v76, v48
	v_mul_f32_e32 v94, v72, v50
	v_mul_f32_e32 v83, v72, v52
	v_mul_f32_e32 v87, v77, v55
	v_mul_f32_e32 v91, v77, v54
	v_mul_f32_e32 v95, v73, v56
	v_mul_f32_e32 v84, v73, v58
	s_waitcnt lgkmcnt(1)
	v_mul_f32_e32 v88, v78, v61
	v_mul_f32_e32 v92, v78, v60
	s_waitcnt lgkmcnt(0)
	v_mul_f32_e32 v96, v74, v62
	v_cvt_pk_bf16_f32 v112, v81, v82
	v_cvt_pk_bf16_f32 v113, v83, v84
	v_cvt_pk_bf16_f32 v114, v85, v86
	v_cvt_pk_bf16_f32 v115, v87, v88
	v_cvt_pk_bf16_f32 v116, v89, v90
	v_cvt_pk_bf16_f32 v117, v91, v92
	v_cvt_pk_bf16_f32 v118, v93, v94
	v_cvt_pk_bf16_f32 v119, v95, v96
	v_cvt_pk_bf16_f32 v120, v45, v51
	v_cvt_pk_bf16_f32 v121, v57, v63
	ds_write_b16 v246, v112 offset:50304
	ds_write_b16_d16_hi v246, v112 offset:50448
	ds_write_b16 v246, v113 offset:50592
	ds_write_b16_d16_hi v246, v113 offset:50736
	ds_write_b16 v246, v114 offset:54912
	ds_write_b16_d16_hi v246, v114 offset:55056
	ds_write_b16 v246, v115 offset:55200
	ds_write_b16_d16_hi v246, v115 offset:55344
	ds_write_b16 v246, v116 offset:57216
	ds_write_b16_d16_hi v246, v116 offset:57360
	ds_write_b16 v246, v117 offset:57504
	ds_write_b16_d16_hi v246, v117 offset:57648
	ds_write_b16 v246, v118 offset:59520
	ds_write_b16_d16_hi v246, v118 offset:59664
	ds_write_b16 v246, v119 offset:59808
	ds_write_b16_d16_hi v246, v119 offset:59952
	ds_write_b64 v139, v[114:115] offset:16
	ds_write_b64 v139, v[116:117] offset:48
	ds_write_b64 v140, v[120:121] offset:48
	s_branch .Lpq1_end
.Lpq1_q3:
	ds_read2st64_b32 v[26:27], v143 offset0:1 offset1:7
	ds_read2st64_b32 v[28:29], v143 offset0:13 offset1:19
	ds_read2st64_b32 v[30:31], v143 offset0:25 offset1:31
	ds_read2st64_b32 v[32:33], v143 offset0:37 offset1:43
	ds_read2st64_b32 v[34:35], v143 offset0:49 offset1:55
	ds_read2st64_b32 v[36:37], v143 offset0:61 offset1:67
	ds_read2st64_b32 v[40:41], v143 offset0:72 offset1:73
	ds_read2st64_b32 v[42:43], v143 offset0:74 offset1:75
	ds_read2st64_b32 v[44:45], v143 offset0:76 offset1:77
	ds_read2st64_b32 v[46:47], v143 offset0:78 offset1:79
	ds_read2st64_b32 v[48:49], v143 offset0:80 offset1:81
	ds_read2st64_b32 v[50:51], v143 offset0:82 offset1:83
	ds_read2st64_b32 v[52:53], v143 offset0:84 offset1:85
	ds_read2st64_b32 v[54:55], v143 offset0:86 offset1:87
	ds_read2st64_b32 v[56:57], v143 offset0:88 offset1:89
	s_waitcnt lgkmcnt(14)
	ds_read2st64_b32 v[58:59], v143 offset0:90 offset1:91
	s_waitcnt lgkmcnt(14)
	ds_read2st64_b32 v[60:61], v143 offset0:92 offset1:93
	s_waitcnt lgkmcnt(14)
	ds_read2st64_b32 v[62:63], v143 offset0:94 offset1:95
	v_add_f32_e32 v69, v26, v27
	v_add_f32_e32 v69, v69, v28
	v_add_f32_e32 v69, v69, v29
	v_add_f32_e32 v69, v69, v30
	v_add_f32_e32 v69, v69, v31
	s_waitcnt lgkmcnt(14)
	v_add_f32_e32 v69, v69, v32
	v_add_f32_e32 v69, v69, v33
	s_waitcnt lgkmcnt(13)
	v_add_f32_e32 v69, v69, v34
	v_add_f32_e32 v69, v69, v35
	s_waitcnt lgkmcnt(12)
	v_add_f32_e32 v69, v69, v36
	v_add_f32_e32 v69, v69, v37
	s_waitcnt lgkmcnt(11)
	v_add_f32_e32 v65, v69, v41
	s_waitcnt lgkmcnt(8)
	v_add_f32_e32 v66, v65, v47
	s_waitcnt lgkmcnt(5)
	v_add_f32_e32 v67, v66, v53
	s_waitcnt lgkmcnt(2)
	v_add_f32_e32 v68, v67, v59
	v_mul_f32_e32 v79, 0xbfb8aa3b, v69
	v_exp_f32_e32 v70, v79
	v_mul_f32_e32 v80, 0x3fb8aa3b, v65
	v_exp_f32_e32 v75, v80
	v_exp_f32_e64 v71, -v80
	v_mul_f32_e32 v97, 0x3fb8aa3b, v66
	v_exp_f32_e32 v76, v97
	v_exp_f32_e64 v72, -v97
	v_mul_f32_e32 v80, 0x3fb8aa3b, v67
	v_exp_f32_e32 v77, v80
	v_exp_f32_e64 v73, -v80
	v_mul_f32_e32 v97, 0x3fb8aa3b, v68
	v_exp_f32_e32 v78, v97
	v_exp_f32_e64 v74, -v97
	s_nop 0
	v_mul_f32_e32 v81, v70, v40
	v_mul_f32_e32 v85, v75, v43
	v_mul_f32_e32 v89, v75, v42
	v_mul_f32_e32 v93, v71, v44
	v_mul_f32_e32 v82, v71, v46
	v_mul_f32_e32 v86, v76, v49
	v_mul_f32_e32 v90, v76, v48
	v_mul_f32_e32 v94, v72, v50
	v_mul_f32_e32 v83, v72, v52
	v_mul_f32_e32 v87, v77, v55
	v_mul_f32_e32 v91, v77, v54
	v_mul_f32_e32 v95, v73, v56
	v_mul_f32_e32 v84, v73, v58
	s_waitcnt lgkmcnt(1)
	v_mul_f32_e32 v88, v78, v61
	v_mul_f32_e32 v92, v78, v60
	s_waitcnt lgkmcnt(0)
	v_mul_f32_e32 v96, v74, v62
	v_cvt_pk_bf16_f32 v112, v81, v82
	v_cvt_pk_bf16_f32 v113, v83, v84
	v_cvt_pk_bf16_f32 v114, v85, v86
	v_cvt_pk_bf16_f32 v115, v87, v88
	v_cvt_pk_bf16_f32 v116, v89, v90
	v_cvt_pk_bf16_f32 v117, v91, v92
	v_cvt_pk_bf16_f32 v118, v93, v94
	v_cvt_pk_bf16_f32 v119, v95, v96
	v_cvt_pk_bf16_f32 v120, v45, v51
	v_cvt_pk_bf16_f32 v121, v57, v63
	ds_write_b16 v246, v112 offset:50880
	ds_write_b16_d16_hi v246, v112 offset:51024
	ds_write_b16 v246, v113 offset:51168
	ds_write_b16_d16_hi v246, v113 offset:51312
	ds_write_b16 v246, v114 offset:55488
	ds_write_b16_d16_hi v246, v114 offset:55632
	ds_write_b16 v246, v115 offset:55776
	ds_write_b16_d16_hi v246, v115 offset:55920
	ds_write_b16 v246, v116 offset:57792
	ds_write_b16_d16_hi v246, v116 offset:57936
	ds_write_b16 v246, v117 offset:58080
	ds_write_b16_d16_hi v246, v117 offset:58224
	ds_write_b16 v246, v118 offset:60096
	ds_write_b16_d16_hi v246, v118 offset:60240
	ds_write_b16 v246, v119 offset:60384
	ds_write_b16_d16_hi v246, v119 offset:60528
	ds_write_b64 v139, v[114:115] offset:24
	ds_write_b64 v139, v[116:117] offset:56
	ds_write_b64 v140, v[120:121] offset:56
	v_add_u32_e32 v123, 0x18d00, v143
	ds_write_b32 v123, v74
	s_branch .Lpq1_end
